# GEMM phase prologues: both batches of first-unit stage DMAs issued together (wait+barrier moved behind the second batch, vmcnt 2 -> 8)
# baseline (speedup 1.0000x reference)
.LBB0_322:
	s_lshl_b32 s15, s14, 5
	s_mov_b64 s[10:11], 0x80
	s_and_b32 s50, s15, 0x60
	s_add_i32 m0, s40, 0x18000
	v_lshl_add_u64 v[8:9], v[8:9], 0, s[10:11]
	s_lshl_b32 s45, s7, 6
	s_lshl_b32 s5, s7, 13
	s_lshl_b32 s20, s50, 7
	global_load_lds_dwordx4 v[8:9], off
	v_lshl_add_u64 v[6:7], v[6:7], 0, s[10:11]
	s_add_i32 m0, s40, 0x1a000
	s_add_i32 s51, s40, 0x8000
	s_add_i32 s52, s40, 0xa000
	global_load_lds_dwordx4 v[6:7], off
	v_lshl_add_u64 v[2:3], v[2:3], 0, s[10:11]
	s_mov_b32 m0, s51
	s_add_u32 s18, s30, 0x40080
	global_load_lds_dwordx4 v[2:3], off
	v_lshl_add_u64 v[2:3], v[4:5], 0, s[10:11]
	s_mov_b32 m0, s52
	s_addc_u32 s19, s31, 0
	global_load_lds_dwordx4 v[2:3], off
	s_add_i32 m0, s40, 0x1c000
	v_lshl_add_u64 v[2:3], s[18:19], 0, v[202:203]
	global_load_lds_dwordx4 v[2:3], off
	v_lshl_add_u64 v[2:3], s[18:19], 0, v[198:199]
	s_add_i32 m0, s40, 0x1e000
	v_lshlrev_b32_e32 v4, 2, v216
	global_load_lds_dwordx4 v[2:3], off
	s_waitcnt vmcnt(8)
	s_barrier
	v_and_b32_e32 v2, 48, v0
	v_lshl_or_b32 v3, v216, 6, v2
	v_or_b32_e32 v2, v217, v2
	v_and_b32_e32 v4, 32, v4
	v_bitop3_b32 v225, s20, v2, v218 bitop3:0xf6
	v_lshlrev_b32_e32 v2, 8, v0
	v_bitop3_b32 v3, v3, s5, v4 bitop3:0xde
	v_and_b32_e32 v2, 0x18000, v2
	v_lshlrev_b32_e32 v4, 11, v12
	v_and_or_b32 v227, v0, 31, s15
	s_lshl_b32 s14, s14, 7
	s_add_i32 s15, 0, 0x21000
	v_or3_b32 v2, v10, v2, v4
	s_add_i32 s14, s15, s14
	v_add_u32_e32 v206, v2, v11
	v_lshlrev_b32_e32 v2, 4, v13
	s_waitcnt vmcnt(6)
	s_cmpk_lt_u32 s6, 0x100
	v_and_b32_e32 v2, 0x38000, v2
	s_cselect_b64 s[18:19], -1, 0
	s_lshl_b32 s6, s7, 8
	v_or3_b32 v2, v10, v2, v4
	s_sext_i32_i16 s2, s4
	v_lshrrev_b32_e32 v224, 4, v252
	v_cmp_gt_u32_e64 s[4:5], 32, v252
	v_lshl_add_u32 v228, v252, 2, s14
	s_add_i32 s14, s15, s6
	s_ashr_i32 s15, s3, 31
	v_mov_b32_e32 v207, v203
	v_add_u32_e32 v208, v2, v11
	v_mov_b32_e32 v209, v203
	v_mov_b64_e32 v[210:211], 0x580
	v_mov_b64_e32 v[212:213], 0x57f
	s_add_i32 s53, 0, 0x10000
	s_add_i32 s54, 0, 0x14000
	v_add_u32_e32 v229, 0, v3
	v_mov_b32_e32 v230, 0x358637bd
	s_movk_i32 s55, 0x1600
	s_barrier
	s_branch .LBB0_325

.LBB0_355:
	s_add_u32 s18, s38, 0xda00000
	s_addc_u32 s19, s39, 0
	s_add_u32 s20, s38, 0x380000
	s_mov_b64 s[22:23], 0x80
	s_addc_u32 s21, s39, 0
	s_and_b32 s40, s6, 3
	s_add_i32 m0, s13, 0x18000
	v_lshl_add_u64 v[8:9], v[8:9], 0, s[22:23]
	s_lshl_b32 s41, s7, 6
	s_lshl_b32 s6, s7, 13
	s_lshl_b32 s7, s40, 5
	s_lshl_b32 s8, s40, 12
	global_load_lds_dwordx4 v[8:9], off
	v_lshl_add_u64 v[6:7], v[6:7], 0, s[22:23]
	s_add_i32 m0, s13, 0x1a000
	s_add_i32 s42, s13, 0x8000
	s_add_i32 s43, s13, 0xa000
	global_load_lds_dwordx4 v[6:7], off
	v_lshl_add_u64 v[2:3], v[2:3], 0, s[22:23]
	s_mov_b32 m0, s42
	s_add_u32 s4, s60, 0x10080
	global_load_lds_dwordx4 v[2:3], off
	v_lshl_add_u64 v[2:3], v[4:5], 0, s[22:23]
	s_mov_b32 m0, s43
	s_addc_u32 s5, s61, 0
	global_load_lds_dwordx4 v[2:3], off
	s_add_i32 m0, s13, 0x1c000
	v_lshl_add_u64 v[2:3], s[4:5], 0, v[132:133]
	global_load_lds_dwordx4 v[2:3], off
	v_lshl_add_u64 v[2:3], s[4:5], 0, v[136:137]
	s_add_i32 m0, s13, 0x1e000
	v_bfe_u32 v146, v0, 4, 2
	global_load_lds_dwordx4 v[2:3], off
	s_waitcnt vmcnt(8)
	s_barrier
	s_cmpk_lt_u32 s2, 0x100
	v_lshlrev_b32_e32 v2, 4, v146
	v_lshlrev_b32_e32 v4, 2, v216
	s_cselect_b64 s[24:25], -1, 0
	s_ashr_i32 s44, s3, 31
	s_ashr_i32 s2, s94, 31
	v_lshl_or_b32 v3, v216, 6, v2
	v_and_b32_e32 v4, 32, v4
	v_or_b32_e32 v2, v2, v217
	s_waitcnt vmcnt(6)
	s_add_u32 s26, s94, s3
	v_bitop3_b32 v3, v3, s6, v4 bitop3:0xde
	v_bitop3_b32 v147, s8, v2, v218 bitop3:0xf6
	s_addc_u32 s27, s2, s44
	s_add_i32 s62, 0, 0x10000
	s_add_i32 s63, 0, 0x14000
	s_mov_b64 s[28:29], 0x100
	v_mov_b64_e32 v[138:139], 0x100
	v_mov_b64_e32 v[140:141], 0xff
	s_mov_b32 s45, 0x2680000
	v_add_u32_e32 v148, s62, v147
	v_add_u32_e32 v149, s63, v147
	v_add_u32_e32 v150, 0, v3
	s_mov_b64 s[30:31], 0x180
	s_lshl_b32 s8, s7, 1
	s_barrier
	s_branch .LBB0_358

.LBB0_607:
	v_and_b32_e32 v14, 15, v0
	v_and_b32_e32 v15, 48, v0
	v_lshlrev_b32_e32 v16, 2, v0
	v_lshl_or_b32 v1, s2, 6, v14
	v_lshl_or_b32 v14, v14, 6, v15
	s_lshl_b32 s2, s2, 13
	v_and_b32_e32 v16, 32, v16
	s_mov_b64 s[20:21], 0x80
	s_and_b32 s30, s4, 3
	v_bitop3_b32 v14, v14, s2, v16 bitop3:0xde
	v_lshlrev_b32_e32 v17, 6, v0
	s_movk_i32 s2, 0x3c0
	s_add_i32 m0, s33, 0x18000
	v_lshl_add_u64 v[8:9], v[8:9], 0, s[20:21]
	v_and_or_b32 v15, v17, s2, v15
	s_lshl_b32 s2, s30, 12
	global_load_lds_dwordx4 v[8:9], off
	v_lshl_add_u64 v[6:7], v[6:7], 0, s[20:21]
	s_add_i32 m0, s33, 0x1a000
	s_add_i32 s42, s33, 0x8000
	s_add_i32 s43, s33, 0xa000
	global_load_lds_dwordx4 v[6:7], off
	v_lshl_add_u64 v[4:5], v[4:5], 0, s[20:21]
	s_mov_b32 m0, s42
	s_add_u32 s6, s24, 0xb0080
	global_load_lds_dwordx4 v[4:5], off
	v_lshl_add_u64 v[2:3], v[2:3], 0, s[20:21]
	s_mov_b32 m0, s43
	s_addc_u32 s7, s25, 0
	global_load_lds_dwordx4 v[2:3], off
	s_add_i32 m0, s33, 0x1c000
	v_lshl_add_u64 v[2:3], s[6:7], 0, v[132:133]
	global_load_lds_dwordx4 v[2:3], off
	v_lshl_add_u64 v[2:3], s[6:7], 0, v[136:137]
	s_add_i32 m0, s33, 0x1e000
	s_sext_i32_i8 s10, s5
	global_load_lds_dwordx4 v[2:3], off
	s_waitcnt vmcnt(8)
	s_barrier
	v_add_u16_e32 v2, v10, v11
	v_lshrrev_b16_e32 v4, 1, v2
	s_mov_b64 s[4:5], 0xb0080
	s_waitcnt vmcnt(6)
	v_add_lshl_u32 v2, v12, v4, 1
	v_mov_b32_e32 v3, v133
	v_lshl_add_u64 v[138:139], v[2:3], 0, s[4:5]
	v_add_lshl_u32 v2, v13, v4, 1
	v_bitop3_b32 v151, s2, v15, v16 bitop3:0xf6
	v_lshl_add_u64 v[140:141], v[2:3], 0, s[4:5]
	v_mov_b64_e32 v[142:143], 0x100
	v_mov_b64_e32 v[144:145], 0xff
	s_add_i32 s44, 0, 0x10000
	s_add_i32 s45, 0, 0x14000
	v_add_u32_e32 v152, 0, v14
	v_mov_b32_e32 v2, v133
	v_mov_b32_e32 v4, v133
	v_mov_b32_e32 v13, v133
	v_mov_b32_e32 v14, v133
	v_mov_b32_e32 v15, v133
	v_mov_b32_e32 v16, v133
	s_barrier

.LBB0_764:
	s_mov_b64 s[20:21], 0x80
	s_and_b32 s74, s1, 3
	s_add_i32 m0, s67, 0x18000
	v_lshl_add_u64 v[10:11], v[10:11], 0, s[20:21]
	s_lshl_b32 s75, s2, 6
	s_lshl_b32 s1, s2, 13
	s_lshl_b32 s2, s74, 12
	global_load_lds_dwordx4 v[10:11], off
	v_lshl_add_u64 v[8:9], v[8:9], 0, s[20:21]
	s_add_i32 m0, s67, 0x1a000
	s_add_i32 s76, s67, 0x8000
	s_add_i32 s77, s67, 0xa000
	global_load_lds_dwordx4 v[8:9], off
	v_lshl_add_u64 v[4:5], v[4:5], 0, s[20:21]
	s_mov_b32 m0, s76
	s_add_u32 s4, s56, 0x40080
	global_load_lds_dwordx4 v[4:5], off
	v_lshl_add_u64 v[4:5], v[6:7], 0, s[20:21]
	s_mov_b32 m0, s77
	s_addc_u32 s5, s57, 0
	global_load_lds_dwordx4 v[4:5], off
	s_add_i32 m0, s67, 0x1c000
	v_lshl_add_u64 v[4:5], s[4:5], 0, v[180:181]
	global_load_lds_dwordx4 v[4:5], off
	v_lshl_add_u64 v[4:5], s[4:5], 0, v[184:185]
	s_add_i32 m0, s67, 0x1e000
	s_cmpk_lt_u32 s0, 0x100
	global_load_lds_dwordx4 v[4:5], off
	s_waitcnt vmcnt(8)
	s_barrier
	s_cselect_b64 s[22:23], -1, 0
	s_add_u32 s24, s38, 0x100000
	v_bfe_u32 v227, v0, 4, 2
	s_addc_u32 s25, s39, 0
	v_and_b32_e32 v1, 15, v0
	v_lshlrev_b32_e32 v4, 4, v227
	v_lshlrev_b32_e32 v6, 2, v0
	s_cmp_eq_u32 s74, 0
	v_lshl_or_b32 v5, v1, 6, v4
	v_and_b32_e32 v6, 32, v6
	s_cselect_b64 s[26:27], -1, 0
	s_lshl_b32 s0, s74, 6
	v_bitop3_b32 v5, v5, s1, v6 bitop3:0xde
	v_lshlrev_b32_e32 v7, 6, v0
	s_movk_i32 s1, 0x3c0
	s_add_u32 s78, s72, s0
	v_and_or_b32 v4, v7, s1, v4
	s_addc_u32 s79, s73, 0
	s_lshl_b32 s1, s74, 2
	s_add_u32 s1, s38, s1
	v_bitop3_b32 v230, s2, v4, v6 bitop3:0xf6
	s_addc_u32 s2, s39, 0
	s_add_u32 s28, s1, 0x340000
	v_lshlrev_b32_e32 v4, 8, v0
	s_addc_u32 s29, s2, 0
	v_and_b32_e32 v4, 0x18000, v4
	v_lshlrev_b32_e32 v6, 11, v13
	s_add_u32 s30, s1, 0x300000
	v_or3_b32 v4, v3, v4, v6
	s_addc_u32 s31, s2, 0
	v_add_u32_e32 v186, v4, v12
	v_lshlrev_b32_e32 v4, 4, v14
	s_waitcnt vmcnt(6)
	s_add_u32 s46, s91, s0
	v_and_b32_e32 v4, 0x38000, v4
	s_addc_u32 s47, s95, 0
	v_or3_b32 v3, v3, v4, v6
	s_add_i32 s84, 0, 0x10000
	s_add_i32 s85, 0, 0x14000
	s_ashr_i32 s82, s3, 31
	s_ashr_i32 s83, s94, 31
	v_mov_b32_e32 v187, v2
	v_add_u32_e32 v188, v3, v12
	v_mov_b32_e32 v189, v2
	v_mov_b64_e32 v[190:191], 0x200
	v_mov_b64_e32 v[192:193], 0x1ff
	v_add_u32_e32 v231, s84, v230
	v_add_u32_e32 v232, s85, v230
	v_add_u32_e32 v233, 0, v5
	s_mov_b32 s86, 0x3200000
	v_mov_b32_e32 v234, 0x358637bd
	s_movk_i32 s87, 0x600
	v_mov_b32_e32 v235, 0x3e38aa3b
	v_mov_b32_e32 v6, 0
	v_mov_b32_e32 v7, v2
	v_mov_b32_e32 v8, v2
	v_mov_b32_e32 v9, v2
	v_mov_b32_e32 v10, 1.0
	s_barrier
	s_branch .LBB0_767

.LBB0_1030:
	s_mov_b64 s[18:19], 0x80
	s_and_b32 s74, s2, 3
	s_add_i32 m0, s66, 0x18000
	v_lshl_add_u64 v[10:11], v[10:11], 0, s[18:19]
	s_lshl_b32 s75, s4, 6
	s_lshl_b32 s2, s4, 13
	s_lshl_b32 s6, s74, 12
	global_load_lds_dwordx4 v[10:11], off
	v_lshl_add_u64 v[8:9], v[8:9], 0, s[18:19]
	s_add_i32 m0, s66, 0x1a000
	s_add_i32 s76, s66, 0x8000
	s_add_i32 s77, s66, 0xa000
	global_load_lds_dwordx4 v[8:9], off
	v_lshl_add_u64 v[4:5], v[4:5], 0, s[18:19]
	s_mov_b32 m0, s76
	s_add_u32 s4, s52, 0x10080
	global_load_lds_dwordx4 v[4:5], off
	v_lshl_add_u64 v[4:5], v[6:7], 0, s[18:19]
	s_mov_b32 m0, s77
	s_addc_u32 s5, s53, 0
	global_load_lds_dwordx4 v[4:5], off
	s_add_i32 m0, s66, 0x1c000
	v_lshl_add_u64 v[4:5], s[4:5], 0, v[184:185]
	global_load_lds_dwordx4 v[4:5], off
	v_lshl_add_u64 v[4:5], s[4:5], 0, v[188:189]
	s_add_i32 m0, s66, 0x1e000
	v_bfe_u32 v212, v0, 4, 2
	global_load_lds_dwordx4 v[4:5], off
	s_waitcnt vmcnt(8)
	s_barrier
	s_cmpk_lt_u32 s1, 0x100
	v_and_b32_e32 v1, 15, v0
	v_lshlrev_b32_e32 v4, 4, v212
	v_lshlrev_b32_e32 v6, 2, v0
	s_cselect_b64 s[20:21], -1, 0
	s_add_u32 s22, s38, 0x100000
	v_lshl_or_b32 v5, v1, 6, v4
	v_and_b32_e32 v6, 32, v6
	s_addc_u32 s23, s39, 0
	v_bitop3_b32 v5, v5, s2, v6 bitop3:0xde
	v_lshlrev_b32_e32 v7, 6, v0
	s_movk_i32 s2, 0x3c0
	s_bitcmp0_b32 s1, 6
	v_and_or_b32 v4, v7, s2, v4
	s_cselect_b64 s[24:25], -1, 0
	s_lshl_b32 s2, s74, 6
	s_or_b32 s78, s2, 0x7ffffd00
	s_lshl_b32 s2, s1, 1
	s_and_b32 s2, s2, 0x80
	s_add_u32 s79, s60, s2
	s_addc_u32 s82, s61, 0
	s_bitcmp1_b32 s1, 6
	s_mul_i32 s1, s74, 0x180
	s_waitcnt vmcnt(6)
	s_cselect_b64 s[26:27], -1, 0
	s_add_u32 s28, s10, s1
	v_bitop3_b32 v213, s6, v4, v6 bitop3:0xf6
	s_addc_u32 s29, s11, 0
	s_add_i32 s85, 0, 0x10000
	s_add_i32 s86, 0, 0x14000
	s_ashr_i32 s83, s3, 31
	s_ashr_i32 s84, s94, 31
	v_add3_u32 v190, v13, v3, v12
	v_mov_b32_e32 v191, v2
	v_add3_u32 v192, v14, v3, v12
	v_mov_b32_e32 v193, v2
	v_mov_b64_e32 v[194:195], 0x1c0
	v_mov_b64_e32 v[196:197], 0x1bf
	v_add_u32_e32 v214, s85, v213
	v_add_u32_e32 v215, s86, v213
	v_add_u32_e32 v216, 0, v5
	s_mov_b32 s87, 0x300000
	v_mov_b32_e32 v217, 0x358637bd
	v_bfrev_b32_e32 v218, 60
	v_mov_b32_e32 v219, 0x3b800000
	v_mov_b32_e32 v6, 1.0
	s_barrier
	s_branch .LBB0_1033

.LBB0_1508:
	s_add_u32 s16, s38, 0xda00000
	s_addc_u32 s17, s39, 0
	s_add_u32 s18, s38, 0x380000
	s_mov_b64 s[20:21], 0x80
	s_addc_u32 s19, s39, 0
	s_and_b32 s41, s6, 3
	s_add_i32 m0, s14, 0x18000
	v_lshl_add_u64 v[8:9], v[8:9], 0, s[20:21]
	s_lshl_b32 s42, s7, 6
	s_lshl_b32 s6, s7, 13
	s_lshl_b32 s7, s41, 5
	s_lshl_b32 s8, s41, 12
	global_load_lds_dwordx4 v[8:9], off
	v_lshl_add_u64 v[6:7], v[6:7], 0, s[20:21]
	s_add_i32 m0, s14, 0x1a000
	s_add_i32 s43, s14, 0x8000
	s_add_i32 s44, s14, 0xa000
	global_load_lds_dwordx4 v[6:7], off
	v_lshl_add_u64 v[2:3], v[2:3], 0, s[20:21]
	s_mov_b32 m0, s43
	s_add_u32 s4, s58, 0x10080
	global_load_lds_dwordx4 v[2:3], off
	v_lshl_add_u64 v[2:3], v[4:5], 0, s[20:21]
	s_mov_b32 m0, s44
	s_addc_u32 s5, s59, 0
	global_load_lds_dwordx4 v[2:3], off
	s_add_i32 m0, s14, 0x1c000
	v_lshl_add_u64 v[2:3], s[4:5], 0, v[132:133]
	global_load_lds_dwordx4 v[2:3], off
	v_lshl_add_u64 v[2:3], s[4:5], 0, v[136:137]
	s_add_i32 m0, s14, 0x1e000
	v_bfe_u32 v146, v0, 4, 2
	global_load_lds_dwordx4 v[2:3], off
	s_waitcnt vmcnt(8)
	s_barrier
	v_lshlrev_b32_e32 v2, 4, v146
	v_lshlrev_b32_e32 v4, 2, v1
	v_lshl_or_b32 v3, v1, 6, v2
	v_and_b32_e32 v4, 32, v4
	v_bitop3_b32 v3, v3, s6, v4 bitop3:0xde
	v_lshlrev_b32_e32 v4, 6, v0
	s_movk_i32 s4, 0x3c0
	s_cmpk_lt_u32 s2, 0x100
	v_and_or_b32 v2, v4, s4, v2
	v_lshlrev_b32_e32 v4, 2, v0
	s_cselect_b64 s[22:23], -1, 0
	s_ashr_i32 s2, s0, 31
	v_and_b32_e32 v4, 32, v4
	s_waitcnt vmcnt(6)
	s_add_u32 s24, s0, 0x80
	v_bitop3_b32 v147, s8, v2, v4 bitop3:0xf6
	s_addc_u32 s25, s2, 0
	s_add_i32 s45, 0, 0x10000
	s_add_i32 s60, 0, 0x14000
	s_mov_b64 s[26:27], 0x100
	v_mov_b64_e32 v[138:139], 0x100
	v_mov_b64_e32 v[140:141], 0xff
	s_mov_b32 s0, 0x2680000
	v_add_u32_e32 v148, s45, v147
	v_add_u32_e32 v149, s60, v147
	v_add_u32_e32 v150, 0, v3
	s_mov_b64 s[28:29], 0x180
	s_lshl_b32 s8, s7, 1
	s_barrier
	s_branch .LBB0_1511

.LBB0_1623:
	v_and_b32_e32 v14, 15, v0
	v_and_b32_e32 v15, 48, v0
	v_lshlrev_b32_e32 v16, 2, v0
	v_lshl_or_b32 v1, s2, 6, v14
	v_lshl_or_b32 v14, v14, 6, v15
	s_lshl_b32 s2, s2, 13
	v_and_b32_e32 v16, 32, v16
	s_mov_b64 s[20:21], 0x80
	s_and_b32 s17, s5, 3
	v_bitop3_b32 v14, v14, s2, v16 bitop3:0xde
	v_lshlrev_b32_e32 v17, 6, v0
	s_movk_i32 s2, 0x3c0
	s_add_i32 m0, s33, 0x18000
	v_lshl_add_u64 v[8:9], v[8:9], 0, s[20:21]
	v_and_or_b32 v15, v17, s2, v15
	s_lshl_b32 s2, s17, 12
	global_load_lds_dwordx4 v[8:9], off
	v_lshl_add_u64 v[6:7], v[6:7], 0, s[20:21]
	s_add_i32 m0, s33, 0x1a000
	s_add_i32 s42, s33, 0x8000
	s_add_i32 s43, s33, 0xa000
	global_load_lds_dwordx4 v[6:7], off
	v_lshl_add_u64 v[4:5], v[4:5], 0, s[20:21]
	s_mov_b32 m0, s42
	s_add_u32 s6, s30, 0x40080
	global_load_lds_dwordx4 v[4:5], off
	v_lshl_add_u64 v[2:3], v[2:3], 0, s[20:21]
	s_mov_b32 m0, s43
	s_addc_u32 s7, s31, 0
	global_load_lds_dwordx4 v[2:3], off
	s_add_i32 m0, s33, 0x1c000
	v_lshl_add_u64 v[2:3], s[6:7], 0, v[132:133]
	global_load_lds_dwordx4 v[2:3], off
	v_lshl_add_u64 v[2:3], s[6:7], 0, v[136:137]
	s_add_i32 m0, s33, 0x1e000
	v_lshlrev_b32_e32 v4, 11, v12
	global_load_lds_dwordx4 v[2:3], off
	s_waitcnt vmcnt(8)
	s_barrier
	v_lshlrev_b32_e32 v2, 8, v0
	v_and_b32_e32 v2, 0x18000, v2
	v_or3_b32 v2, v10, v2, v4
	s_sext_i32_i8 s10, s4
	s_mov_b64 s[4:5], 0x40080
	v_add_u32_e32 v2, v2, v11
	v_mov_b32_e32 v3, v133
	v_lshl_add_u64 v[138:139], v[2:3], 0, s[4:5]
	v_lshlrev_b32_e32 v2, 4, v13
	v_and_b32_e32 v2, 0x38000, v2
	s_waitcnt vmcnt(6)
	v_or3_b32 v2, v10, v2, v4
	v_add_u32_e32 v2, v2, v11
	v_bitop3_b32 v151, s2, v15, v16 bitop3:0xf6
	v_lshl_add_u64 v[140:141], v[2:3], 0, s[4:5]
	v_mov_b64_e32 v[142:143], 0x100
	v_mov_b64_e32 v[144:145], 0xff
	s_add_i32 s44, 0, 0x10000
	s_add_i32 s45, 0, 0x14000
	v_add_u32_e32 v152, 0, v14
	v_mov_b32_e32 v2, v133
	v_mov_b32_e32 v4, v133
	v_mov_b32_e32 v10, v133
	v_mov_b32_e32 v11, v133
	v_mov_b32_e32 v13, v133
	v_mov_b32_e32 v14, v133
	v_mov_b32_e32 v15, v133
	v_mov_b32_e32 v16, v133
	s_barrier

.LBB0_1758:
	s_lshl_b32 s15, s14, 5
	s_mov_b64 s[16:17], 0x80
	s_and_b32 s50, s15, 0x60
	s_add_i32 m0, s40, 0x18000
	v_lshl_add_u64 v[8:9], v[8:9], 0, s[16:17]
	s_lshl_b32 s45, s7, 6
	s_lshl_b32 s5, s7, 13
	s_lshl_b32 s20, s50, 7
	global_load_lds_dwordx4 v[8:9], off
	v_lshl_add_u64 v[6:7], v[6:7], 0, s[16:17]
	s_add_i32 m0, s40, 0x1a000
	s_add_i32 s51, s40, 0x8000
	s_add_i32 s52, s40, 0xa000
	global_load_lds_dwordx4 v[6:7], off
	v_lshl_add_u64 v[2:3], v[2:3], 0, s[16:17]
	s_mov_b32 m0, s51
	s_add_u32 s18, s30, 0x40080
	global_load_lds_dwordx4 v[2:3], off
	v_lshl_add_u64 v[2:3], v[4:5], 0, s[16:17]
	s_mov_b32 m0, s52
	s_addc_u32 s19, s31, 0
	global_load_lds_dwordx4 v[2:3], off
	s_add_i32 m0, s40, 0x1c000
	v_lshl_add_u64 v[2:3], s[18:19], 0, v[202:203]
	global_load_lds_dwordx4 v[2:3], off
	v_lshl_add_u64 v[2:3], s[18:19], 0, v[198:199]
	s_add_i32 m0, s40, 0x1e000
	s_sext_i32_i16 s2, s4
	global_load_lds_dwordx4 v[2:3], off
	s_waitcnt vmcnt(8)
	s_barrier
	v_and_b32_e32 v1, 15, v0
	v_and_b32_e32 v2, 48, v0
	v_lshlrev_b32_e32 v4, 2, v0
	v_lshlrev_b32_e32 v5, 6, v0
	s_movk_i32 s4, 0x3c0
	v_lshl_or_b32 v3, v1, 6, v2
	v_and_b32_e32 v4, 32, v4
	v_and_or_b32 v2, v5, s4, v2
	v_bitop3_b32 v217, s20, v2, v4 bitop3:0xf6
	v_lshlrev_b32_e32 v2, 8, v0
	v_bitop3_b32 v3, v3, s5, v4 bitop3:0xde
	v_and_b32_e32 v2, 0x18000, v2
	v_lshlrev_b32_e32 v4, 11, v13
	v_and_or_b32 v218, v0, 31, s15
	s_lshl_b32 s14, s14, 7
	s_add_i32 s15, 0, 0x21000
	v_or3_b32 v2, v11, v2, v4
	s_add_i32 s14, s15, s14
	v_add_u32_e32 v206, v2, v12
	v_lshlrev_b32_e32 v2, 4, v10
	s_waitcnt vmcnt(6)
	s_cmpk_lt_u32 s6, 0x100
	v_and_b32_e32 v2, 0x38000, v2
	s_cselect_b64 s[18:19], -1, 0
	s_lshl_b32 s6, s7, 8
	v_or3_b32 v2, v11, v2, v4
	v_lshrrev_b32_e32 v216, 4, v252
	v_cmp_gt_u32_e64 s[4:5], 32, v252
	v_lshl_add_u32 v219, v252, 2, s14
	s_add_i32 s14, s15, s6
	s_ashr_i32 s15, s3, 31
	v_mov_b32_e32 v207, v203
	v_add_u32_e32 v208, v2, v12
	v_mov_b32_e32 v209, v203
	v_mov_b64_e32 v[210:211], 0x580
	v_mov_b64_e32 v[212:213], 0x57f
	s_add_i32 s53, 0, 0x10000
	s_add_i32 s54, 0, 0x14000
	v_add_u32_e32 v220, 0, v3
	v_mov_b32_e32 v221, 0x358637bd
	s_movk_i32 s55, 0x1600
	s_barrier
	s_branch .LBB0_1761

.LBB0_1882:
	v_and_b32_e32 v14, 15, v0
	v_and_b32_e32 v15, 48, v0
	v_lshlrev_b32_e32 v16, 2, v0
	v_lshl_or_b32 v1, s2, 6, v14
	v_lshl_or_b32 v14, v14, 6, v15
	s_lshl_b32 s2, s2, 13
	v_and_b32_e32 v16, 32, v16
	s_mov_b64 s[20:21], 0x80
	s_and_b32 s30, s4, 3
	v_bitop3_b32 v14, v14, s2, v16 bitop3:0xde
	v_lshlrev_b32_e32 v17, 6, v0
	s_movk_i32 s2, 0x3c0
	s_add_i32 m0, s33, 0x18000
	v_lshl_add_u64 v[8:9], v[8:9], 0, s[20:21]
	v_and_or_b32 v15, v17, s2, v15
	s_lshl_b32 s2, s30, 12
	global_load_lds_dwordx4 v[8:9], off
	v_lshl_add_u64 v[6:7], v[6:7], 0, s[20:21]
	s_add_i32 m0, s33, 0x1a000
	s_add_i32 s42, s33, 0x8000
	s_add_i32 s43, s33, 0xa000
	global_load_lds_dwordx4 v[6:7], off
	v_lshl_add_u64 v[4:5], v[4:5], 0, s[20:21]
	s_mov_b32 m0, s42
	s_add_u32 s6, s24, 0xb0080
	global_load_lds_dwordx4 v[4:5], off
	v_lshl_add_u64 v[2:3], v[2:3], 0, s[20:21]
	s_mov_b32 m0, s43
	s_addc_u32 s7, s25, 0
	global_load_lds_dwordx4 v[2:3], off
	s_add_i32 m0, s33, 0x1c000
	v_lshl_add_u64 v[2:3], s[6:7], 0, v[132:133]
	global_load_lds_dwordx4 v[2:3], off
	v_lshl_add_u64 v[2:3], s[6:7], 0, v[136:137]
	s_add_i32 m0, s33, 0x1e000
	s_sext_i32_i8 s16, s5
	global_load_lds_dwordx4 v[2:3], off
	s_waitcnt vmcnt(8)
	s_barrier
	v_add_u16_e32 v2, v10, v11
	v_lshrrev_b16_e32 v4, 1, v2
	s_mov_b64 s[4:5], 0xb0080
	s_waitcnt vmcnt(6)
	v_add_lshl_u32 v2, v12, v4, 1
	v_mov_b32_e32 v3, v133
	v_lshl_add_u64 v[138:139], v[2:3], 0, s[4:5]
	v_add_lshl_u32 v2, v13, v4, 1
	v_bitop3_b32 v151, s2, v15, v16 bitop3:0xf6
	v_lshl_add_u64 v[140:141], v[2:3], 0, s[4:5]
	v_mov_b64_e32 v[142:143], 0x100
	v_mov_b64_e32 v[144:145], 0xff
	s_add_i32 s44, 0, 0x10000
	s_add_i32 s45, 0, 0x14000
	v_add_u32_e32 v152, 0, v14
	v_mov_b32_e32 v2, v133
	v_mov_b32_e32 v4, v133
	v_mov_b32_e32 v13, v133
	v_mov_b32_e32 v14, v133
	v_mov_b32_e32 v15, v133
	v_mov_b32_e32 v16, v133
	s_barrier

.LBB0_2023:
	s_lshl_b32 s48, s0, 6
	s_lshl_b32 s14, s0, 13
	s_lshl_b32 s0, s1, 5
	s_and_b32 s49, s0, 0x60
	s_lshl_b32 s15, s49, 7
	s_add_u32 s8, s38, 0xda00000
	s_addc_u32 s9, s39, 0
	s_add_u32 s12, s38, 0x380000
	s_mov_b64 s[16:17], 0x80
	s_addc_u32 s13, s39, 0
	s_add_i32 m0, s29, 0x18000
	v_lshl_add_u64 v[8:9], v[8:9], 0, s[16:17]
	global_load_lds_dwordx4 v[8:9], off
	v_lshl_add_u64 v[6:7], v[6:7], 0, s[16:17]
	s_add_i32 m0, s29, 0x1a000
	s_add_i32 s50, s29, 0x8000
	s_add_i32 s51, s29, 0xa000
	global_load_lds_dwordx4 v[6:7], off
	v_lshl_add_u64 v[4:5], v[4:5], 0, s[16:17]
	s_mov_b32 m0, s50
	s_add_u32 s0, s34, 0x40080
	global_load_lds_dwordx4 v[4:5], off
	v_lshl_add_u64 v[2:3], v[2:3], 0, s[16:17]
	s_mov_b32 m0, s51
	s_addc_u32 s1, s35, 0
	global_load_lds_dwordx4 v[2:3], off
	s_add_i32 m0, s29, 0x1c000
	v_lshl_add_u64 v[2:3], s[0:1], 0, v[162:163]
	global_load_lds_dwordx4 v[2:3], off
	v_lshl_add_u64 v[2:3], s[0:1], 0, v[166:167]
	s_add_i32 m0, s29, 0x1e000
	v_bfe_u32 v231, v0, 4, 2
	global_load_lds_dwordx4 v[2:3], off
	s_waitcnt vmcnt(8)
	s_barrier
	v_and_b32_e32 v229, 15, v0
	v_lshlrev_b32_e32 v2, 4, v231
	v_lshlrev_b32_e32 v4, 2, v0
	v_lshlrev_b32_e32 v5, 6, v0
	s_movk_i32 s0, 0x3c0
	v_lshl_or_b32 v3, v229, 6, v2
	v_and_b32_e32 v4, 32, v4
	v_and_or_b32 v2, v5, s0, v2
	v_lshlrev_b32_e32 v0, 8, v0
	v_bitop3_b32 v201, s15, v2, v4 bitop3:0xf6
	v_and_b32_e32 v0, 0x18000, v0
	v_lshlrev_b32_e32 v2, 11, v11
	v_or3_b32 v0, v1, v0, v2
	v_add_u32_e32 v168, v0, v10
	v_lshlrev_b32_e32 v0, 4, v12
	s_waitcnt vmcnt(6)
	v_and_b32_e32 v0, 0x38000, v0
	v_bitop3_b32 v3, v3, s14, v4 bitop3:0xde
	v_or3_b32 v0, v1, v0, v2
	s_add_i32 s55, 0, 0x10000
	s_add_i32 s56, 0, 0x14000
	s_sext_i32_i8 s2, s18
	s_mov_b32 s52, 0x18000
	s_mov_b32 s53, 0x8000
	s_ashr_i32 s54, s3, 31
	v_mov_b32_e32 v169, v163
	v_add_u32_e32 v170, v0, v10
	v_mov_b32_e32 v171, v163
	v_mov_b64_e32 v[252:253], 0x100
	v_add_u32_e32 v203, s55, v201
	v_add_u32_e32 v207, s56, v201
	v_add_u32_e32 v209, 0, v3
	s_mov_b32 s18, 0xbfb8aa3b
	v_mov_b32_e32 v213, 0x358637bd
	s_mov_b32 s57, 0x40000
	s_mov_b32 s58, 0x48000
	s_mov_b32 s59, 0x50000
	s_mov_b32 s60, 0x58000
	s_barrier
